# attention: next-tile K-fragment reads back inside the PV phase (MFMA gaps), first exp group + V k-step 0/1 prefetch stay in the QK phase
# speedup vs baseline: 1.0049x; 1.0049x over previous
.Lattn_ldsbL:
	s_add_i32 s33, s65, 0x10000
	s_and_b32 s33, s33, 0x18000
	s_add_i32 s33, s57, s33
	v_lshlrev_b32_e32 v198, 1, v150
	v_mfma_f32_32x32x16_bf16 v[32:47], v[242:245], v[64:67], v[32:47]
	v_exp_f32_e32 v72, v72
	v_exp_f32_e32 v73, v73
	v_exp_f32_e32 v74, v74
	v_exp_f32_e32 v75, v75
	v_add_f32_e32 v184, v72, v73
	s_add_i32 s100, s65, 0
	s_and_b32 s100, s100, 0x18000
	v_add_u32_e32 v194, s100, v149
	v_add_u32_e32 v195, v194, v157
	s_mov_b32 m0, s33
	s_nop 0
	global_load_lds_dwordx4 v188, s[70:71]
	v_mfma_f32_32x32x16_bf16 v[48:63], v[246:249], v[64:67], v[48:63]
	v_exp_f32_e32 v76, v76
	v_exp_f32_e32 v77, v77
	v_cvt_pk_bf16_f32 v68, v72, v73
	v_add_f32_e32 v185, v74, v75
	v_cvt_pk_bf16_f32 v69, v74, v75
	v_add_u32_e32 v196, v194, v193
	v_add_u32_e32 v197, v194, v208
	v_add_u32_e32 v194, v194, v209
	ds_read_b128 v[132:135], v195
	v_mfma_f32_32x32x16_bf16 v[16:31], v[250:253], v[64:67], v[16:31]
	v_exp_f32_e32 v78, v78
	v_exp_f32_e32 v79, v79
	v_add_f32_e32 v186, v76, v77
	v_cvt_pk_bf16_f32 v70, v76, v77
	v_add_f32_e32 v184, v184, v185
	ds_read_b128 v[116:119], v195 offset:4096
	ds_read_b128 v[136:139], v196
	ds_read_b128 v[120:123], v196 offset:4096
	ds_read_b128 v[140:143], v197
	s_add_u32 s100, s70, 0x40000
	s_addc_u32 s101, s71, 0
	s_add_i32 m0, s33, 0x2000
	s_nop 0
	global_load_lds_dwordx4 v188, s[100:101]
	v_mfma_f32_32x32x16_bf16 v[0:15], v[200:203], v[64:67], v[0:15]
	v_add_f32_e32 v187, v78, v79
	v_cvt_pk_bf16_f32 v71, v78, v79
	v_add_f32_e32 v186, v186, v187
	v_add_f32_e32 v184, v184, v186
	v_add_f32_e32 v206, v206, v184
	ds_read_b128 v[124:127], v197 offset:4096
	ds_read_b128 v[128:131], v194
	ds_read_b128 v[112:115], v194 offset:4096
	ds_read_b128 v[242:245], v218 offset:16384
	ds_read_b128 v[246:249], v218 offset:20480
	ds_read_b128 v[250:253], v218 offset:24576
	ds_read_b128 v[200:203], v218 offset:28672
	v_mfma_f32_32x32x16_bf16 v[32:47], v[220:223], v[68:71], v[32:47]
	v_exp_f32_e32 v80, v80
	v_exp_f32_e32 v81, v81
	v_exp_f32_e32 v82, v82
	v_exp_f32_e32 v83, v83
	v_add_f32_e32 v184, v80, v81
	s_add_i32 m0, s33, 0x4000
	s_nop 0
	global_load_lds_dwordx4 v198, s[66:67]
	v_mfma_f32_32x32x16_bf16 v[48:63], v[224:227], v[68:71], v[48:63]
	v_exp_f32_e32 v84, v84
	v_exp_f32_e32 v85, v85
	v_cvt_pk_bf16_f32 v72, v80, v81
	v_add_f32_e32 v185, v82, v83
	v_cvt_pk_bf16_f32 v73, v82, v83
	v_mfma_f32_32x32x16_bf16 v[16:31], v[234:237], v[68:71], v[16:31]
	v_exp_f32_e32 v86, v86
	v_exp_f32_e32 v87, v87
	v_add_f32_e32 v186, v84, v85
	v_cvt_pk_bf16_f32 v74, v84, v85
	v_add_f32_e32 v184, v184, v185
	s_add_u32 s100, s66, 0x40000
	s_addc_u32 s101, s67, 0
	s_add_i32 m0, s33, 0x6000
	s_nop 0
	global_load_lds_dwordx4 v198, s[100:101]
	v_mfma_f32_32x32x16_bf16 v[0:15], v[238:241], v[68:71], v[0:15]
	v_add_f32_e32 v187, v86, v87
	v_cvt_pk_bf16_f32 v75, v86, v87
	v_add_f32_e32 v186, v186, v187
	v_add_f32_e32 v184, v184, v186
	v_add_f32_e32 v206, v206, v184
	ds_read_b128 v[220:223], v219 offset:16384
	ds_read_b128 v[224:227], v219 offset:20480
	ds_read_b128 v[234:237], v219 offset:24576
	ds_read_b128 v[238:241], v219 offset:28672
	s_waitcnt lgkmcnt(4)
	v_mfma_f32_32x32x16_bf16 v[32:47], v[242:245], v[72:75], v[32:47]
	v_exp_f32_e32 v88, v88
	v_exp_f32_e32 v89, v89
	v_exp_f32_e32 v90, v90
	v_exp_f32_e32 v91, v91
	v_add_f32_e32 v184, v88, v89
	s_add_u32 s100, s70, 0x1000
	s_addc_u32 s101, s71, 0
	s_add_i32 m0, s33, 0x1000
	s_nop 0
	global_load_lds_dwordx4 v188, s[100:101]
	v_mfma_f32_32x32x16_bf16 v[48:63], v[246:249], v[72:75], v[48:63]
	v_exp_f32_e32 v92, v92
	v_exp_f32_e32 v93, v93
	v_cvt_pk_bf16_f32 v76, v88, v89
	v_add_f32_e32 v185, v90, v91
	v_cvt_pk_bf16_f32 v77, v90, v91
	v_mfma_f32_32x32x16_bf16 v[16:31], v[250:253], v[72:75], v[16:31]
	v_exp_f32_e32 v94, v94
	v_exp_f32_e32 v95, v95
	v_add_f32_e32 v186, v92, v93
	v_cvt_pk_bf16_f32 v78, v92, v93
	v_add_f32_e32 v184, v184, v185
	s_add_u32 s100, s70, 0x41000
	s_addc_u32 s101, s71, 0
	s_add_i32 m0, s33, 0x3000
	s_nop 0
	global_load_lds_dwordx4 v188, s[100:101]
	v_mfma_f32_32x32x16_bf16 v[0:15], v[200:203], v[72:75], v[0:15]
	v_add_f32_e32 v187, v94, v95
	v_cvt_pk_bf16_f32 v79, v94, v95
	v_add_f32_e32 v186, v186, v187
	v_add_f32_e32 v184, v184, v186
	v_add_f32_e32 v206, v206, v184
	s_waitcnt lgkmcnt(0)
	v_mfma_f32_32x32x16_bf16 v[32:47], v[220:223], v[76:79], v[32:47]
	s_add_u32 s100, s66, 0x20000
	s_addc_u32 s101, s67, 0
	s_add_i32 m0, s33, 0x5000
	s_nop 0
	global_load_lds_dwordx4 v198, s[100:101]
	v_mfma_f32_32x32x16_bf16 v[48:63], v[224:227], v[76:79], v[48:63]
	s_add_u32 s100, s66, 0x60000
	s_addc_u32 s101, s67, 0
	s_add_i32 m0, s33, 0x7000
	s_nop 0
	global_load_lds_dwordx4 v198, s[100:101]
	s_waitcnt lgkmcnt(0)
	s_barrier
	s_add_i32 s65, s65, 0x8000
	s_addk_i32 s23, 0x100
	s_add_i32 s36, s36, 64
	s_cmpk_eq_i32 s23, 0x1e00
	v_mfma_f32_32x32x16_bf16 v[16:31], v[234:237], v[76:79], v[16:31]
	v_mfma_f32_32x32x16_bf16 v[0:15], v[238:241], v[76:79], v[0:15]
	s_cbranch_scc1 .Lattn_exit
	s_branch .Lattn_tail
.LBB0_280:
	v_mfma_f32_32x32x16_bf16 v[32:47], v[242:245], v[64:67], v[32:47]
	v_exp_f32_e32 v72, v72
	v_exp_f32_e32 v73, v73
	v_exp_f32_e32 v74, v74
	v_exp_f32_e32 v75, v75
	v_add_f32_e32 v184, v72, v73
	s_add_i32 s100, s65, 0
	s_and_b32 s100, s100, 0x18000
	v_add_u32_e32 v194, s100, v149
	v_add_u32_e32 v195, v194, v157
	v_mfma_f32_32x32x16_bf16 v[48:63], v[246:249], v[64:67], v[48:63]
	v_exp_f32_e32 v76, v76
	v_exp_f32_e32 v77, v77
	v_cvt_pk_bf16_f32 v68, v72, v73
	v_add_f32_e32 v185, v74, v75
	v_cvt_pk_bf16_f32 v69, v74, v75
	v_add_u32_e32 v196, v194, v193
	v_add_u32_e32 v197, v194, v208
	v_add_u32_e32 v194, v194, v209
	ds_read_b128 v[132:135], v195
	v_mfma_f32_32x32x16_bf16 v[16:31], v[250:253], v[64:67], v[16:31]
	v_exp_f32_e32 v78, v78
	v_exp_f32_e32 v79, v79
	v_add_f32_e32 v186, v76, v77
	v_cvt_pk_bf16_f32 v70, v76, v77
	v_add_f32_e32 v184, v184, v185
	ds_read_b128 v[116:119], v195 offset:4096
	ds_read_b128 v[136:139], v196
	ds_read_b128 v[120:123], v196 offset:4096
	ds_read_b128 v[140:143], v197
	v_mfma_f32_32x32x16_bf16 v[0:15], v[200:203], v[64:67], v[0:15]
	v_add_f32_e32 v187, v78, v79
	v_cvt_pk_bf16_f32 v71, v78, v79
	v_add_f32_e32 v186, v186, v187
	v_add_f32_e32 v184, v184, v186
	v_add_f32_e32 v206, v206, v184
	ds_read_b128 v[124:127], v197 offset:4096
	ds_read_b128 v[128:131], v194
	ds_read_b128 v[112:115], v194 offset:4096
	ds_read_b128 v[242:245], v218 offset:16384
	ds_read_b128 v[246:249], v218 offset:20480
	ds_read_b128 v[250:253], v218 offset:24576
	ds_read_b128 v[200:203], v218 offset:28672
	v_mfma_f32_32x32x16_bf16 v[32:47], v[220:223], v[68:71], v[32:47]
	v_exp_f32_e32 v80, v80
	v_exp_f32_e32 v81, v81
	v_exp_f32_e32 v82, v82
	v_exp_f32_e32 v83, v83
	v_add_f32_e32 v184, v80, v81
	v_mfma_f32_32x32x16_bf16 v[48:63], v[224:227], v[68:71], v[48:63]
	v_exp_f32_e32 v84, v84
	v_exp_f32_e32 v85, v85
	v_cvt_pk_bf16_f32 v72, v80, v81
	v_add_f32_e32 v185, v82, v83
	v_cvt_pk_bf16_f32 v73, v82, v83
	v_mfma_f32_32x32x16_bf16 v[16:31], v[234:237], v[68:71], v[16:31]
	v_exp_f32_e32 v86, v86
	v_exp_f32_e32 v87, v87
	v_add_f32_e32 v186, v84, v85
	v_cvt_pk_bf16_f32 v74, v84, v85
	v_add_f32_e32 v184, v184, v185
	v_mfma_f32_32x32x16_bf16 v[0:15], v[238:241], v[68:71], v[0:15]
	v_add_f32_e32 v187, v86, v87
	v_cvt_pk_bf16_f32 v75, v86, v87
	v_add_f32_e32 v186, v186, v187
	v_add_f32_e32 v184, v184, v186
	v_add_f32_e32 v206, v206, v184
	ds_read_b128 v[220:223], v219 offset:16384
	ds_read_b128 v[224:227], v219 offset:20480
	ds_read_b128 v[234:237], v219 offset:24576
	ds_read_b128 v[238:241], v219 offset:28672
	s_waitcnt lgkmcnt(4)
	v_mfma_f32_32x32x16_bf16 v[32:47], v[242:245], v[72:75], v[32:47]
	v_exp_f32_e32 v88, v88
	v_exp_f32_e32 v89, v89
	v_exp_f32_e32 v90, v90
	v_exp_f32_e32 v91, v91
	v_add_f32_e32 v184, v88, v89
	v_mfma_f32_32x32x16_bf16 v[48:63], v[246:249], v[72:75], v[48:63]
	v_exp_f32_e32 v92, v92
	v_exp_f32_e32 v93, v93
	v_cvt_pk_bf16_f32 v76, v88, v89
	v_add_f32_e32 v185, v90, v91
	v_cvt_pk_bf16_f32 v77, v90, v91
	v_mfma_f32_32x32x16_bf16 v[16:31], v[250:253], v[72:75], v[16:31]
	v_exp_f32_e32 v94, v94
	v_exp_f32_e32 v95, v95
	v_add_f32_e32 v186, v92, v93
	v_cvt_pk_bf16_f32 v78, v92, v93
	v_add_f32_e32 v184, v184, v185
	v_mfma_f32_32x32x16_bf16 v[0:15], v[200:203], v[72:75], v[0:15]
	v_add_f32_e32 v187, v94, v95
	v_cvt_pk_bf16_f32 v79, v94, v95
	v_add_f32_e32 v186, v186, v187
	v_add_f32_e32 v184, v184, v186
	v_add_f32_e32 v206, v206, v184
	s_waitcnt lgkmcnt(0)
	v_mfma_f32_32x32x16_bf16 v[32:47], v[220:223], v[76:79], v[32:47]
	v_mfma_f32_32x32x16_bf16 v[48:63], v[224:227], v[76:79], v[48:63]
	s_waitcnt lgkmcnt(0)
	s_barrier
	s_add_i32 s65, s65, 0x8000
	s_addk_i32 s23, 0x100
	s_add_i32 s36, s36, 64
	s_cmpk_eq_i32 s23, 0x1e00
	v_mfma_f32_32x32x16_bf16 v[16:31], v[234:237], v[76:79], v[16:31]
	v_mfma_f32_32x32x16_bf16 v[0:15], v[238:241], v[76:79], v[0:15]
	s_cbranch_scc1 .Lattn_exit

.Lattn_exit:
	s_branch .LBB0_284
.LBB0_282:
	s_waitcnt vmcnt(0) lgkmcnt(0)
	s_barrier
	s_cbranch_execnz .LBB0_278
